# S5 GLU phase moved onto the hand-written 256x128-tile GEMM engine (K=256, own ticket scheduler)
# baseline (speedup 1.0000x reference)
; __device__ __forceinline__ int otid() { int t = threadIdx.x; asm volatile("" : "+v"(t)); return t; }
; __device__ __forceinline__ int frag_off(int fr, int fq) { return (fr >> 3) * 1024 + (fr & 7) * 128 + ((fq ^ ((fr >> 1) & 7)) << 4); }
;   const int tid = otid(), lane = tid & 63, wid = tid >> 6, wr = wid >> 1, wc = wid & 1, fr = lane & 15, fq = lane >> 4;
;   const int o0 = tid * 16;
;   const int lrow = (o0 >> 10) * 8 + ((o0 >> 7) & 7), lcol = ((((o0 >> 4) & 7) ^ ((lrow >> 1) & 7))) * 8;
;   const bf16_t* ag = A + (size_t)lrow * lda + lcol;
;   const bf16_t* bg = Bt + (size_t)lrow * ldb + lcol;
;   const char* A8 = (const char*)A;
;   const char* B8 = (const char*)Bt;
;   unsigned aoff[4], boff[NT];
; #pragma unroll
;   for (int i = 0; i < 4; ++i) aoff[i] = (unsigned)(((lrow + 32 * i) * lda + lcol) * 2);
; #pragma unroll
;   for (int i = 0; i < NT; ++i) boff[i] = (unsigned)(((lrow + (i & 1) * bs1 + (i >> 1) * bs2) * ldb + lcol) * 2);
;   const int wbase = __builtin_amdgcn_readfirstlane(wid) * 1024;
;   const int inner = frag_off(fr, fq);
;   const int abase = wr * 8192 + inner;
;   const int bbase = 16384 + wc * (NT * 2048) + inner;
;   const int nk = K >> 6;
; __device__ __forceinline__ void phase_glu(const Params& p, int mrows, char* smem) {
;   TILE_IDS; (void)tid;
;   bf16_t* P = WS_BF(p, OFF_P);
;   const bf16_t* W = WS_BF(p, OFF_W) + W_GLU;
;   for (TileIter ti(mrows / 128, 4, 4, 4); ti.valid(); ti.next()) {
;     int tm, tn; ti.get(tm, tn);
;     f32x4 acc[4][4];
;     zero_acc<4>(acc);
;     gemm_main<4>(P + (size_t)tm * 128 * PC + C_S5G, PC, W + (size_t)tn * 128 * 256, 256, 256, acc, smem);
;     bf16_t* ob = P + (size_t)(tm * 128 + wr * 64 + fr) * PC + C_YS5 + tn * 64 + wc * 32 + fq * 4;
.LBB0_89:
	s_andn2_b64 vcc, exec, s[40:41]
	s_cbranch_vccnz .LBB0_93
	s_waitcnt vmcnt(0) lgkmcnt(0)
	s_lshr_b32 s23, s22, 9
	s_lshl_b32 s98, s91, 3
	s_lshl_b64 s[36:37], s[98:99], 2
	v_readlane_b32 s42, v251, 3
	s_nop 3
	s_add_u32 s36, s42, s36
	v_readlane_b32 s42, v251, 4
	s_nop 3
	s_addc_u32 s37, s42, s37
	v_readfirstlane_b32 s40, v92
	v_readfirstlane_b32 s41, v93
	v_readfirstlane_b32 s42, v94
	v_readfirstlane_b32 s43, v95
	v_readfirstlane_b32 s44, v96
	v_readfirstlane_b32 s45, v97
	v_readfirstlane_b32 s46, v98
	v_readfirstlane_b32 s47, v99
	v_writelane_b32 v249, s40, 0
	v_writelane_b32 v249, s41, 1
	v_writelane_b32 v249, s42, 2
	v_writelane_b32 v249, s43, 3
	v_writelane_b32 v249, s44, 4
	v_writelane_b32 v249, s45, 5
	v_writelane_b32 v249, s46, 6
	v_writelane_b32 v249, s47, 7
	v_readfirstlane_b32 s40, v100
	v_readfirstlane_b32 s41, v101
	v_readfirstlane_b32 s42, v102
	v_readfirstlane_b32 s43, v103
	v_readfirstlane_b32 s44, v104
	v_readfirstlane_b32 s45, v105
	v_readfirstlane_b32 s46, v106
	v_readfirstlane_b32 s47, v107
	v_writelane_b32 v249, s40, 8
	v_writelane_b32 v249, s41, 9
	v_writelane_b32 v249, s42, 10
	v_writelane_b32 v249, s43, 11
	v_writelane_b32 v249, s44, 12
	v_writelane_b32 v249, s45, 13
	v_writelane_b32 v249, s46, 14
	v_writelane_b32 v249, s47, 15
	v_readfirstlane_b32 s40, v108
	v_readfirstlane_b32 s41, v109
	v_readfirstlane_b32 s42, v110
	v_readfirstlane_b32 s43, v111
	v_readfirstlane_b32 s44, v112
	v_readfirstlane_b32 s45, v113
	v_readfirstlane_b32 s46, v114
	v_readfirstlane_b32 s47, v115
	v_writelane_b32 v249, s40, 16
	v_writelane_b32 v249, s41, 17
	v_writelane_b32 v249, s42, 18
	v_writelane_b32 v249, s43, 19
	v_writelane_b32 v249, s44, 20
	v_writelane_b32 v249, s45, 21
	v_writelane_b32 v249, s46, 22
	v_writelane_b32 v249, s47, 23
	v_readfirstlane_b32 s40, v116
	v_readfirstlane_b32 s41, v117
	v_readfirstlane_b32 s42, v118
	v_readfirstlane_b32 s43, v119
	v_readfirstlane_b32 s44, v120
	v_readfirstlane_b32 s45, v121
	v_readfirstlane_b32 s46, v122
	v_readfirstlane_b32 s47, v123
	v_writelane_b32 v249, s40, 24
	v_writelane_b32 v249, s41, 25
	v_writelane_b32 v249, s42, 26
	v_writelane_b32 v249, s43, 27
	v_writelane_b32 v249, s44, 28
	v_writelane_b32 v249, s45, 29
	v_writelane_b32 v249, s46, 30
	v_writelane_b32 v249, s47, 31
	v_readfirstlane_b32 s40, v124
	v_readfirstlane_b32 s41, v125
	v_readfirstlane_b32 s42, v126
	v_readfirstlane_b32 s43, v127
	v_readfirstlane_b32 s44, v128
	v_readfirstlane_b32 s45, v129
	v_readfirstlane_b32 s46, v130
	v_readfirstlane_b32 s47, v131
	v_writelane_b32 v249, s40, 32
	v_writelane_b32 v249, s41, 33
	v_writelane_b32 v249, s42, 34
	v_writelane_b32 v249, s43, 35
	v_writelane_b32 v249, s44, 36
	v_writelane_b32 v249, s45, 37
	v_writelane_b32 v249, s46, 38
	v_writelane_b32 v249, s47, 39
	v_readfirstlane_b32 s40, v132
	v_readfirstlane_b32 s41, v133
	s_nop 1
	v_writelane_b32 v249, s40, 40
	v_writelane_b32 v249, s41, 41
	v_readfirstlane_b32 s100, v90
	v_readfirstlane_b32 s101, v91
	v_lshrrev_b32_e32 v238, 4, v172
	v_and_b32_e32 v238, 7, v238
	v_and_b32_e32 v239, 7, v172
	v_xor_b32_e32 v238, v238, v239
	v_lshlrev_b32_e32 v238, 4, v238
	v_lshrrev_b32_e32 v239, 3, v172
	v_lshl_or_b32 v228, v239, 11, v238
	v_and_b32_e32 v238, 15, v172
	v_lshrrev_b32_e32 v239, 1, v238
	v_and_b32_e32 v239, 7, v239
	v_bfe_u32 v240, v172, 4, 2
	v_xor_b32_e32 v239, v239, v240
	v_lshlrev_b32_e32 v239, 4, v239
	v_and_b32_e32 v240, 7, v238
	v_lshl_or_b32 v239, v240, 7, v239
	v_lshrrev_b32_e32 v240, 3, v238
	v_lshl_or_b32 v239, v240, 10, v239
	v_lshrrev_b32_e32 v240, 7, v172
	v_lshl_or_b32 v231, v240, 14, v239
	v_bfe_u32 v240, v172, 6, 1
	v_lshl_or_b32 v232, v240, 13, v239
	v_add_u32_e32 v232, 0x10000, v232
	v_xor_b32_e32 v235, 64, v231
	v_xor_b32_e32 v236, 64, v232
	v_readfirstlane_b32 s46, v172
	s_nop 3
	s_lshr_b32 s46, s46, 6
	s_lshl_b32 s46, s46, 10
	v_lshrrev_b32_e32 v238, 4, v172
	v_and_b32_e32 v238, 7, v238
	v_and_b32_e32 v239, 7, v172
	v_xor_b32_e32 v238, v238, v239
	v_lshlrev_b32_e32 v238, 4, v238
	v_lshrrev_b32_e32 v239, 3, v172
	s_movk_i32 s45, 0x1820
	v_mad_u32_u24 v228, v239, s45, v238
	v_lshl_or_b32 v237, v239, 9, v238
	v_lshrrev_b32_e32 v238, 7, v172
	v_and_b32_e32 v239, 15, v172
	v_lshl_or_b32 v238, v238, 7, v239
	v_bfe_u32 v239, v172, 6, 1
	v_bfe_u32 v240, v172, 4, 2
	v_lshlrev_b32_e32 v240, 3, v240
	v_lshl_or_b32 v239, v239, 6, v240
	v_mad_u32_u24 v234, v238, s45, v239
	s_mov_b32 s44, s39

;     ...
; #pragma unroll
;   for (int i = 0; i < 4; ++i) __builtin_amdgcn_global_load_lds((const unsigned*)(ag + (size_t)(32 * i) * lda), (unsigned*)(smem + i * 4096 + o0), 16, 0, 0);
; #pragma unroll
;   for (int i = 0; i < NT; ++i) __builtin_amdgcn_global_load_lds((const unsigned*)(bg + (size_t)((i & 1) * bs1 + (i >> 1) * bs2) * ldb), (unsigned*)(smem + 16384 + i * 4096 + o0), 16, 0, 0);
;   asm volatile("s_waitcnt vmcnt(0)" ::: "memory");
;   __syncthreads();
;   for (int kt = 0; kt < nk; ++kt) {
;     const int cur = (kt & 1) * 32768, nxt = 32768 - cur;
;     if (kt + 1 < nk) {
; #pragma unroll
;       for (int i = 0; i < 4; ++i)
;         __builtin_amdgcn_global_load_lds((const unsigned*)(A8 + (size_t)(kt + 1) * 128 + aoff[i]), (unsigned*)(smem + nxt + i * 4096 + wbase), 16, 0, 0);
; #pragma unroll
;       for (int i = 0; i < NT; ++i)
;         __builtin_amdgcn_global_load_lds((const unsigned*)(B8 + (size_t)(kt + 1) * 128 + boff[i]), (unsigned*)(smem + nxt + 16384 + i * 4096 + wbase), 16, 0, 0);
;     }
;     __builtin_amdgcn_sched_barrier(0);
;     if (LEAN) {
; #pragma unroll
;       for (int ks = 0; ks < 2; ++ks) {
;         bf16x8 af[4], bfr[NT];
; #pragma unroll
;         for (int m = 0; m < 4; ++m) af[m] = *(const bf16x8*)(smem + cur + ((abase + m * 2048) ^ (ks * 64)));
; #pragma unroll
;         for (int n = 0; n < NT; ++n) bfr[n] = *(const bf16x8*)(smem + cur + ((bbase + n * 2048) ^ (ks * 64)));
;         __builtin_amdgcn_s_setprio(1);
; #pragma unroll
;         for (int m = 0; m < 4; ++m)
; #pragma unroll
;           for (int n = 0; n < NT; ++n) acc[m][n] = __builtin_amdgcn_mfma_f32_16x16x32_bf16(bfr[n], af[m], acc[m][n], 0, 0, 0);
;         __builtin_amdgcn_s_setprio(0);
;       }
;     } else {
;     bf16x8 af0[4], bf0[NT], af1[4], bf1[NT];
; #pragma unroll
;     for (int m = 0; m < 4; ++m) af0[m] = *(const bf16x8*)(smem + cur + (abase + m * 2048));
; #pragma unroll
;     for (int n = 0; n < NT; ++n) bf0[n] = *(const bf16x8*)(smem + cur + (bbase + n * 2048));
; #pragma unroll
;     for (int m = 0; m < 4; ++m) af1[m] = *(const bf16x8*)(smem + cur + ((abase + m * 2048) ^ 64));
; #pragma unroll
;     for (int n = 0; n < NT; ++n) bf1[n] = *(const bf16x8*)(smem + cur + ((bbase + n * 2048) ^ 64));
;     __builtin_amdgcn_sched_barrier(0);
;     __builtin_amdgcn_s_setprio(1);
; #pragma unroll
;     for (int m = 0; m < 4; ++m)
; #pragma unroll
.Lgl_tk0:
	s_or_b64 exec, exec, s[48:49]
	s_lshr_b32 s47, s44, 2
	s_lshl_b32 s47, s47, 3
	s_add_i32 s47, s47, s72
	s_and_b32 s98, s44, 3
	s_mul_i32 s45, s47, 0x182000
	s_mul_hi_u32 s48, s47, 0x182000
	s_add_u32 s40, s100, s45
	s_addc_u32 s41, s101, s48
	s_add_u32 s40, s40, 0x8b80200
	s_addc_u32 s41, s41, 0
	s_lshl_b32 s48, s98, 16
	s_add_u32 s42, s100, s48
	s_addc_u32 s43, s101, 0
	s_add_u32 s42, s42, 0x3340000
	s_addc_u32 s43, s43, 0
	s_add_i32 m0, s46, 0x0
	s_nop 0
	global_load_lds_dwordx4 v228, s[40:41]
	v_add_u32_e32 v230, 0x30400, v228
	s_add_i32 m0, s46, 0x1000
	s_nop 0
	global_load_lds_dwordx4 v230, s[40:41]
	v_add_u32_e32 v230, 0x60800, v228
	s_add_i32 m0, s46, 0x2000
	s_nop 0
	global_load_lds_dwordx4 v230, s[40:41]
	v_add_u32_e32 v230, 0x90c00, v228
	s_add_i32 m0, s46, 0x3000
	s_nop 0
	global_load_lds_dwordx4 v230, s[40:41]
	v_add_u32_e32 v230, 0xc1000, v228
	s_add_i32 m0, s46, 0x4000
	s_nop 0
	global_load_lds_dwordx4 v230, s[40:41]
	v_add_u32_e32 v230, 0xf1400, v228
	s_add_i32 m0, s46, 0x5000
	s_nop 0
	global_load_lds_dwordx4 v230, s[40:41]
	v_add_u32_e32 v230, 0x121800, v228
	s_add_i32 m0, s46, 0x6000
	s_nop 0
	global_load_lds_dwordx4 v230, s[40:41]
	v_add_u32_e32 v230, 0x151c00, v228
	s_add_i32 m0, s46, 0x7000
	s_nop 0
	global_load_lds_dwordx4 v230, s[40:41]
	s_add_i32 m0, s46, 0x10000
	s_nop 0
	global_load_lds_dwordx4 v237, s[42:43]
	v_add_u32_e32 v230, 0x4000, v237
	s_add_i32 m0, s46, 0x11000
	s_nop 0
	global_load_lds_dwordx4 v230, s[42:43]
	v_add_u32_e32 v230, 0x8000, v237
	s_add_i32 m0, s46, 0x12000
	s_nop 0
	global_load_lds_dwordx4 v230, s[42:43]
	v_add_u32_e32 v230, 0xc000, v237
	s_add_i32 m0, s46, 0x13000
	s_nop 0
	global_load_lds_dwordx4 v230, s[42:43]
	v_mov_b64_e32 v[2:3], 0
	v_mov_b64_e32 v[4:5], 0
	v_mov_b64_e32 v[6:7], 0
	v_mov_b64_e32 v[8:9], 0
	v_mov_b64_e32 v[10:11], 0
	v_mov_b64_e32 v[12:13], 0
	v_mov_b64_e32 v[14:15], 0
	v_mov_b64_e32 v[16:17], 0
	v_mov_b64_e32 v[18:19], 0
	v_mov_b64_e32 v[20:21], 0
	v_mov_b64_e32 v[22:23], 0
	v_mov_b64_e32 v[24:25], 0
	v_mov_b64_e32 v[26:27], 0
	v_mov_b64_e32 v[28:29], 0
	v_mov_b64_e32 v[30:31], 0
	v_mov_b64_e32 v[32:33], 0
	v_mov_b64_e32 v[34:35], 0
	v_mov_b64_e32 v[36:37], 0
	v_mov_b64_e32 v[38:39], 0
	v_mov_b64_e32 v[40:41], 0
	v_mov_b64_e32 v[42:43], 0
	v_mov_b64_e32 v[44:45], 0
	v_mov_b64_e32 v[46:47], 0
	v_mov_b64_e32 v[48:49], 0
	v_mov_b64_e32 v[50:51], 0
	v_mov_b64_e32 v[52:53], 0
	v_mov_b64_e32 v[54:55], 0
	v_mov_b64_e32 v[56:57], 0
	v_mov_b64_e32 v[58:59], 0
	v_mov_b64_e32 v[60:61], 0
	v_mov_b64_e32 v[62:63], 0
	v_mov_b64_e32 v[64:65], 0
	v_mov_b64_e32 v[66:67], 0
	v_mov_b64_e32 v[68:69], 0
	v_mov_b64_e32 v[70:71], 0
	v_mov_b64_e32 v[72:73], 0
	v_mov_b64_e32 v[74:75], 0
	v_mov_b64_e32 v[76:77], 0
	v_mov_b64_e32 v[78:79], 0
	v_mov_b64_e32 v[80:81], 0
	v_mov_b64_e32 v[82:83], 0
	v_mov_b64_e32 v[84:85], 0
	v_mov_b64_e32 v[86:87], 0
	v_mov_b64_e32 v[88:89], 0
	v_mov_b64_e32 v[92:93], 0
	v_mov_b64_e32 v[94:95], 0
	v_mov_b64_e32 v[96:97], 0
	v_mov_b64_e32 v[98:99], 0
	v_mov_b64_e32 v[100:101], 0
	v_mov_b64_e32 v[102:103], 0
	v_mov_b64_e32 v[104:105], 0
	v_mov_b64_e32 v[106:107], 0
	v_mov_b64_e32 v[108:109], 0
	v_mov_b64_e32 v[110:111], 0
	v_mov_b64_e32 v[112:113], 0
	v_mov_b64_e32 v[114:115], 0
	v_mov_b64_e32 v[116:117], 0
	v_mov_b64_e32 v[118:119], 0
	v_mov_b64_e32 v[120:121], 0
	v_mov_b64_e32 v[122:123], 0
	v_mov_b64_e32 v[124:125], 0
	v_mov_b64_e32 v[126:127], 0
	v_mov_b64_e32 v[128:129], 0
	v_mov_b64_e32 v[130:131], 0
	s_waitcnt vmcnt(0)
	s_barrier
	ds_read_b128 v[136:139], v232
	ds_read_b128 v[140:143], v232 offset:2048
	ds_read_b128 v[144:147], v232 offset:4096
	ds_read_b128 v[148:151], v232 offset:6144
	ds_read_b128 v[196:199], v231
	ds_read_b128 v[200:203], v231 offset:2048
	ds_read_b128 v[204:207], v231 offset:4096
	ds_read_b128 v[208:211], v231 offset:6144
	ds_read_b128 v[152:155], v236
	ds_read_b128 v[156:159], v236 offset:2048
	ds_read_b128 v[160:163], v236 offset:4096
	ds_read_b128 v[164:167], v236 offset:6144
	ds_read_b128 v[212:215], v231 offset:8192
	ds_read_b128 v[216:219], v231 offset:10240
	ds_read_b128 v[220:223], v231 offset:12288
	ds_read_b128 v[224:227], v231 offset:14336
	s_setprio 1
	s_waitcnt lgkmcnt(8)
	v_mfma_f32_16x16x32_bf16 v[2:5], v[136:139], v[196:199], v[2:5]
	v_mfma_f32_16x16x32_bf16 v[6:9], v[140:143], v[196:199], v[6:9]
	v_mfma_f32_16x16x32_bf16 v[10:13], v[144:147], v[196:199], v[10:13]
	v_mfma_f32_16x16x32_bf16 v[14:17], v[148:151], v[196:199], v[14:17]
	v_mfma_f32_16x16x32_bf16 v[18:21], v[136:139], v[200:203], v[18:21]
	v_mfma_f32_16x16x32_bf16 v[22:25], v[140:143], v[200:203], v[22:25]
	v_mfma_f32_16x16x32_bf16 v[26:29], v[144:147], v[200:203], v[26:29]
	v_mfma_f32_16x16x32_bf16 v[30:33], v[148:151], v[200:203], v[30:33]
	v_mfma_f32_16x16x32_bf16 v[34:37], v[136:139], v[204:207], v[34:37]
	v_mfma_f32_16x16x32_bf16 v[38:41], v[140:143], v[204:207], v[38:41]
	v_mfma_f32_16x16x32_bf16 v[42:45], v[144:147], v[204:207], v[42:45]
	v_mfma_f32_16x16x32_bf16 v[46:49], v[148:151], v[204:207], v[46:49]
	v_mfma_f32_16x16x32_bf16 v[50:53], v[136:139], v[208:211], v[50:53]
	v_mfma_f32_16x16x32_bf16 v[54:57], v[140:143], v[208:211], v[54:57]
	v_mfma_f32_16x16x32_bf16 v[58:61], v[144:147], v[208:211], v[58:61]
	v_mfma_f32_16x16x32_bf16 v[62:65], v[148:151], v[208:211], v[62:65]
	s_waitcnt lgkmcnt(0)
	s_barrier
;     ...
;   for (int kt = 0; kt < nk; ++kt) {
;     const int cur = (kt & 1) * 32768, nxt = 32768 - cur;
;     if (kt + 1 < nk) {
; #pragma unroll
;       for (int i = 0; i < 4; ++i)
;         __builtin_amdgcn_global_load_lds((const unsigned*)(A8 + (size_t)(kt + 1) * 128 + aoff[i]), (unsigned*)(smem + nxt + i * 4096 + wbase), 16, 0, 0);
; #pragma unroll
;       for (int i = 0; i < NT; ++i)
;         __builtin_amdgcn_global_load_lds((const unsigned*)(B8 + (size_t)(kt + 1) * 128 + boff[i]), (unsigned*)(smem + nxt + 16384 + i * 4096 + wbase), 16, 0, 0);
;     }
;     __builtin_amdgcn_sched_barrier(0);
;     if (LEAN) {
; #pragma unroll
;       for (int ks = 0; ks < 2; ++ks) {
;         bf16x8 af[4], bfr[NT];
; #pragma unroll
;         for (int m = 0; m < 4; ++m) af[m] = *(const bf16x8*)(smem + cur + ((abase + m * 2048) ^ (ks * 64)));
; #pragma unroll
;         for (int n = 0; n < NT; ++n) bfr[n] = *(const bf16x8*)(smem + cur + ((bbase + n * 2048) ^ (ks * 64)));
;         __builtin_amdgcn_s_setprio(1);
; #pragma unroll
;         for (int m = 0; m < 4; ++m)
; #pragma unroll
;           for (int n = 0; n < NT; ++n) acc[m][n] = __builtin_amdgcn_mfma_f32_16x16x32_bf16(bfr[n], af[m], acc[m][n], 0, 0, 0);
;         __builtin_amdgcn_s_setprio(0);
;       }
;     } else {
;     bf16x8 af0[4], bf0[NT], af1[4], bf1[NT];
; #pragma unroll
;     for (int m = 0; m < 4; ++m) af0[m] = *(const bf16x8*)(smem + cur + (abase + m * 2048));
; #pragma unroll
;     for (int n = 0; n < NT; ++n) bf0[n] = *(const bf16x8*)(smem + cur + (bbase + n * 2048));
; #pragma unroll
;     for (int m = 0; m < 4; ++m) af1[m] = *(const bf16x8*)(smem + cur + ((abase + m * 2048) ^ 64));
; #pragma unroll
;     for (int n = 0; n < NT; ++n) bf1[n] = *(const bf16x8*)(smem + cur + ((bbase + n * 2048) ^ 64));
;     __builtin_amdgcn_sched_barrier(0);
;     __builtin_amdgcn_s_setprio(1);
; #pragma unroll
;     for (int m = 0; m < 4; ++m)
; #pragma unroll
;       for (int n = 0; n < NT; ++n) acc[m][n] = __builtin_amdgcn_mfma_f32_16x16x32_bf16(bf0[n], af0[m], acc[m][n], 0, 0, 0);
; #pragma unroll
;     for (int m = 0; m < 4; ++m)
; #pragma unroll
;       for (int n = 0; n < NT; ++n) acc[m][n] = __builtin_amdgcn_mfma_f32_16x16x32_bf16(bf1[n], af1[m], acc[m][n], 0, 0, 0);
;     __builtin_amdgcn_s_setprio(0);
;     }
;     __builtin_amdgcn_sched_barrier(0);
;     asm volatile("s_waitcnt vmcnt(0)" ::: "memory");
	s_add_u32 s40, s40, 0x80
	s_addc_u32 s41, s41, 0
	s_add_u32 s42, s42, 0x80
	s_addc_u32 s43, s43, 0
	ds_read_b128 v[196:199], v235
	ds_read_b128 v[200:203], v235 offset:2048
	ds_read_b128 v[204:207], v235 offset:4096
	ds_read_b128 v[208:211], v235 offset:6144
	s_add_i32 m0, s46, 0x8000
	v_mfma_f32_16x16x32_bf16 v[66:69], v[136:139], v[212:215], v[66:69]
	global_load_lds_dwordx4 v228, s[40:41]
	v_add_u32_e32 v230, 0x30400, v228
	s_add_i32 m0, s46, 0x9000
	v_mfma_f32_16x16x32_bf16 v[70:73], v[140:143], v[212:215], v[70:73]
	global_load_lds_dwordx4 v230, s[40:41]
	v_add_u32_e32 v230, 0x60800, v228
	s_add_i32 m0, s46, 0xa000
	v_mfma_f32_16x16x32_bf16 v[74:77], v[144:147], v[212:215], v[74:77]
	global_load_lds_dwordx4 v230, s[40:41]
	v_add_u32_e32 v230, 0x90c00, v228
	s_add_i32 m0, s46, 0xb000
	v_mfma_f32_16x16x32_bf16 v[78:81], v[148:151], v[212:215], v[78:81]
	global_load_lds_dwordx4 v230, s[40:41]
	v_add_u32_e32 v230, 0xc1000, v228
	s_add_i32 m0, s46, 0xc000
	v_mfma_f32_16x16x32_bf16 v[82:85], v[136:139], v[216:219], v[82:85]
	global_load_lds_dwordx4 v230, s[40:41]
	v_add_u32_e32 v230, 0xf1400, v228
	s_add_i32 m0, s46, 0xd000
	v_mfma_f32_16x16x32_bf16 v[86:89], v[140:143], v[216:219], v[86:89]
	global_load_lds_dwordx4 v230, s[40:41]
	v_add_u32_e32 v230, 0x121800, v228
	s_add_i32 m0, s46, 0xe000
	v_mfma_f32_16x16x32_bf16 v[92:95], v[144:147], v[216:219], v[92:95]
	global_load_lds_dwordx4 v230, s[40:41]
	v_add_u32_e32 v230, 0x151c00, v228
	s_add_i32 m0, s46, 0xf000
	v_mfma_f32_16x16x32_bf16 v[96:99], v[148:151], v[216:219], v[96:99]
	global_load_lds_dwordx4 v230, s[40:41]
	s_add_i32 m0, s46, 0x10000
	v_mfma_f32_16x16x32_bf16 v[100:103], v[136:139], v[220:223], v[100:103]
	global_load_lds_dwordx4 v237, s[42:43]
	v_add_u32_e32 v230, 0x4000, v237
	s_add_i32 m0, s46, 0x11000
	v_mfma_f32_16x16x32_bf16 v[104:107], v[140:143], v[220:223], v[104:107]
	global_load_lds_dwordx4 v230, s[42:43]
	v_add_u32_e32 v230, 0x8000, v237
	s_add_i32 m0, s46, 0x12000
	v_mfma_f32_16x16x32_bf16 v[108:111], v[144:147], v[220:223], v[108:111]
	global_load_lds_dwordx4 v230, s[42:43]
	v_add_u32_e32 v230, 0xc000, v237
	s_add_i32 m0, s46, 0x13000
	v_mfma_f32_16x16x32_bf16 v[112:115], v[148:151], v[220:223], v[112:115]
	global_load_lds_dwordx4 v230, s[42:43]
	v_mfma_f32_16x16x32_bf16 v[116:119], v[136:139], v[224:227], v[116:119]
	v_mfma_f32_16x16x32_bf16 v[120:123], v[140:143], v[224:227], v[120:123]
	v_mfma_f32_16x16x32_bf16 v[124:127], v[144:147], v[224:227], v[124:127]
	v_mfma_f32_16x16x32_bf16 v[128:131], v[148:151], v[224:227], v[128:131]
	ds_read_b128 v[212:215], v235 offset:8192
	ds_read_b128 v[216:219], v235 offset:10240
	ds_read_b128 v[220:223], v235 offset:12288
	ds_read_b128 v[224:227], v235 offset:14336
	s_waitcnt lgkmcnt(4)
	v_mfma_f32_16x16x32_bf16 v[2:5], v[152:155], v[196:199], v[2:5]
	v_mfma_f32_16x16x32_bf16 v[6:9], v[156:159], v[196:199], v[6:9]
	v_mfma_f32_16x16x32_bf16 v[10:13], v[160:163], v[196:199], v[10:13]
	v_mfma_f32_16x16x32_bf16 v[14:17], v[164:167], v[196:199], v[14:17]
	v_mfma_f32_16x16x32_bf16 v[18:21], v[152:155], v[200:203], v[18:21]
	v_mfma_f32_16x16x32_bf16 v[22:25], v[156:159], v[200:203], v[22:25]
	v_mfma_f32_16x16x32_bf16 v[26:29], v[160:163], v[200:203], v[26:29]
	v_mfma_f32_16x16x32_bf16 v[30:33], v[164:167], v[200:203], v[30:33]
	v_mfma_f32_16x16x32_bf16 v[34:37], v[152:155], v[204:207], v[34:37]
	v_mfma_f32_16x16x32_bf16 v[38:41], v[156:159], v[204:207], v[38:41]
	v_mfma_f32_16x16x32_bf16 v[42:45], v[160:163], v[204:207], v[42:45]
	v_mfma_f32_16x16x32_bf16 v[46:49], v[164:167], v[204:207], v[46:49]
	v_mfma_f32_16x16x32_bf16 v[50:53], v[152:155], v[208:211], v[50:53]
	v_mfma_f32_16x16x32_bf16 v[54:57], v[156:159], v[208:211], v[54:57]
	v_mfma_f32_16x16x32_bf16 v[58:61], v[160:163], v[208:211], v[58:61]
	v_mfma_f32_16x16x32_bf16 v[62:65], v[164:167], v[208:211], v[62:65]
	s_waitcnt lgkmcnt(0)
	v_mfma_f32_16x16x32_bf16 v[66:69], v[152:155], v[212:215], v[66:69]
	v_mfma_f32_16x16x32_bf16 v[70:73], v[156:159], v[212:215], v[70:73]
	v_mfma_f32_16x16x32_bf16 v[74:77], v[160:163], v[212:215], v[74:77]
	v_mfma_f32_16x16x32_bf16 v[78:81], v[164:167], v[212:215], v[78:81]
	v_mfma_f32_16x16x32_bf16 v[82:85], v[152:155], v[216:219], v[82:85]
	v_mfma_f32_16x16x32_bf16 v[86:89], v[156:159], v[216:219], v[86:89]
	v_mfma_f32_16x16x32_bf16 v[92:95], v[160:163], v[216:219], v[92:95]
	v_mfma_f32_16x16x32_bf16 v[96:99], v[164:167], v[216:219], v[96:99]
	v_mfma_f32_16x16x32_bf16 v[100:103], v[152:155], v[220:223], v[100:103]
	v_mfma_f32_16x16x32_bf16 v[104:107], v[156:159], v[220:223], v[104:107]
	v_mfma_f32_16x16x32_bf16 v[108:111], v[160:163], v[220:223], v[108:111]
	v_mfma_f32_16x16x32_bf16 v[112:115], v[164:167], v[220:223], v[112:115]
	v_mfma_f32_16x16x32_bf16 v[116:119], v[152:155], v[224:227], v[116:119]
	v_mfma_f32_16x16x32_bf16 v[120:123], v[156:159], v[224:227], v[120:123]
	v_mfma_f32_16x16x32_bf16 v[124:127], v[160:163], v[224:227], v[124:127]
	v_mfma_f32_16x16x32_bf16 v[128:131], v[164:167], v[224:227], v[128:131]
	s_setprio 0
	s_waitcnt vmcnt(0)
	s_barrier
;     ...
;   for (int kt = 0; kt < nk; ++kt) {
;     const int cur = (kt & 1) * 32768, nxt = 32768 - cur;
;     if (kt + 1 < nk) {
; #pragma unroll
;       for (int i = 0; i < 4; ++i)
;         __builtin_amdgcn_global_load_lds((const unsigned*)(A8 + (size_t)(kt + 1) * 128 + aoff[i]), (unsigned*)(smem + nxt + i * 4096 + wbase), 16, 0, 0);
; #pragma unroll
;       for (int i = 0; i < NT; ++i)
;         __builtin_amdgcn_global_load_lds((const unsigned*)(B8 + (size_t)(kt + 1) * 128 + boff[i]), (unsigned*)(smem + nxt + 16384 + i * 4096 + wbase), 16, 0, 0);
;     }
;     __builtin_amdgcn_sched_barrier(0);
;     if (LEAN) {
; #pragma unroll
;       for (int ks = 0; ks < 2; ++ks) {
;         bf16x8 af[4], bfr[NT];
; #pragma unroll
;         for (int m = 0; m < 4; ++m) af[m] = *(const bf16x8*)(smem + cur + ((abase + m * 2048) ^ (ks * 64)));
; #pragma unroll
;         for (int n = 0; n < NT; ++n) bfr[n] = *(const bf16x8*)(smem + cur + ((bbase + n * 2048) ^ (ks * 64)));
;         __builtin_amdgcn_s_setprio(1);
; #pragma unroll
;         for (int m = 0; m < 4; ++m)
; #pragma unroll
;           for (int n = 0; n < NT; ++n) acc[m][n] = __builtin_amdgcn_mfma_f32_16x16x32_bf16(bfr[n], af[m], acc[m][n], 0, 0, 0);
;         __builtin_amdgcn_s_setprio(0);
;       }
;     } else {
;     bf16x8 af0[4], bf0[NT], af1[4], bf1[NT];
; #pragma unroll
;     for (int m = 0; m < 4; ++m) af0[m] = *(const bf16x8*)(smem + cur + (abase + m * 2048));
; #pragma unroll
;     for (int n = 0; n < NT; ++n) bf0[n] = *(const bf16x8*)(smem + cur + (bbase + n * 2048));
; #pragma unroll
;     for (int m = 0; m < 4; ++m) af1[m] = *(const bf16x8*)(smem + cur + ((abase + m * 2048) ^ 64));
; #pragma unroll
;     for (int n = 0; n < NT; ++n) bf1[n] = *(const bf16x8*)(smem + cur + ((bbase + n * 2048) ^ 64));
;     __builtin_amdgcn_sched_barrier(0);
;     __builtin_amdgcn_s_setprio(1);
; #pragma unroll
;     for (int m = 0; m < 4; ++m)
; #pragma unroll
;       for (int n = 0; n < NT; ++n) acc[m][n] = __builtin_amdgcn_mfma_f32_16x16x32_bf16(bf0[n], af0[m], acc[m][n], 0, 0, 0);
; #pragma unroll
;     for (int m = 0; m < 4; ++m)
; #pragma unroll
;       for (int n = 0; n < NT; ++n) acc[m][n] = __builtin_amdgcn_mfma_f32_16x16x32_bf16(bf1[n], af1[m], acc[m][n], 0, 0, 0);
;     __builtin_amdgcn_s_setprio(0);
;     }
;     __builtin_amdgcn_sched_barrier(0);
;     asm volatile("s_waitcnt vmcnt(0)" ::: "memory");
	ds_read_b128 v[136:139], v232
	ds_read_b128 v[140:143], v232 offset:2048
	ds_read_b128 v[144:147], v232 offset:4096
	ds_read_b128 v[148:151], v232 offset:6144
	ds_read_b128 v[196:199], v231 offset:32768
	ds_read_b128 v[200:203], v231 offset:34816
	ds_read_b128 v[204:207], v231 offset:36864
	ds_read_b128 v[208:211], v231 offset:38912
	ds_read_b128 v[152:155], v236
	ds_read_b128 v[156:159], v236 offset:2048
	ds_read_b128 v[160:163], v236 offset:4096
	ds_read_b128 v[164:167], v236 offset:6144
	ds_read_b128 v[212:215], v231 offset:40960
	ds_read_b128 v[216:219], v231 offset:43008
	ds_read_b128 v[220:223], v231 offset:45056
	ds_read_b128 v[224:227], v231 offset:47104
	s_setprio 1
	s_waitcnt lgkmcnt(8)
	v_mfma_f32_16x16x32_bf16 v[2:5], v[136:139], v[196:199], v[2:5]
	v_mfma_f32_16x16x32_bf16 v[6:9], v[140:143], v[196:199], v[6:9]
	v_mfma_f32_16x16x32_bf16 v[10:13], v[144:147], v[196:199], v[10:13]
	v_mfma_f32_16x16x32_bf16 v[14:17], v[148:151], v[196:199], v[14:17]
	v_mfma_f32_16x16x32_bf16 v[18:21], v[136:139], v[200:203], v[18:21]
	v_mfma_f32_16x16x32_bf16 v[22:25], v[140:143], v[200:203], v[22:25]
	v_mfma_f32_16x16x32_bf16 v[26:29], v[144:147], v[200:203], v[26:29]
	v_mfma_f32_16x16x32_bf16 v[30:33], v[148:151], v[200:203], v[30:33]
	v_mfma_f32_16x16x32_bf16 v[34:37], v[136:139], v[204:207], v[34:37]
	v_mfma_f32_16x16x32_bf16 v[38:41], v[140:143], v[204:207], v[38:41]
	v_mfma_f32_16x16x32_bf16 v[42:45], v[144:147], v[204:207], v[42:45]
	v_mfma_f32_16x16x32_bf16 v[46:49], v[148:151], v[204:207], v[46:49]
	v_mfma_f32_16x16x32_bf16 v[50:53], v[136:139], v[208:211], v[50:53]
	v_mfma_f32_16x16x32_bf16 v[54:57], v[140:143], v[208:211], v[54:57]
	v_mfma_f32_16x16x32_bf16 v[58:61], v[144:147], v[208:211], v[58:61]
	v_mfma_f32_16x16x32_bf16 v[62:65], v[148:151], v[208:211], v[62:65]
	s_waitcnt lgkmcnt(0)
	s_barrier
	s_add_u32 s40, s40, 0x80
	s_addc_u32 s41, s41, 0
	s_add_u32 s42, s42, 0x80
	s_addc_u32 s43, s43, 0
	ds_read_b128 v[196:199], v235 offset:32768
	ds_read_b128 v[200:203], v235 offset:34816
	ds_read_b128 v[204:207], v235 offset:36864
	ds_read_b128 v[208:211], v235 offset:38912
	s_add_i32 m0, s46, 0x0
	v_mfma_f32_16x16x32_bf16 v[66:69], v[136:139], v[212:215], v[66:69]
	global_load_lds_dwordx4 v228, s[40:41]
	v_add_u32_e32 v230, 0x30400, v228
	s_add_i32 m0, s46, 0x1000
	v_mfma_f32_16x16x32_bf16 v[70:73], v[140:143], v[212:215], v[70:73]
	global_load_lds_dwordx4 v230, s[40:41]
	v_add_u32_e32 v230, 0x60800, v228
	s_add_i32 m0, s46, 0x2000
	v_mfma_f32_16x16x32_bf16 v[74:77], v[144:147], v[212:215], v[74:77]
	global_load_lds_dwordx4 v230, s[40:41]
	v_add_u32_e32 v230, 0x90c00, v228
	s_add_i32 m0, s46, 0x3000
	v_mfma_f32_16x16x32_bf16 v[78:81], v[148:151], v[212:215], v[78:81]
	global_load_lds_dwordx4 v230, s[40:41]
	v_add_u32_e32 v230, 0xc1000, v228
	s_add_i32 m0, s46, 0x4000
	v_mfma_f32_16x16x32_bf16 v[82:85], v[136:139], v[216:219], v[82:85]
	global_load_lds_dwordx4 v230, s[40:41]
	v_add_u32_e32 v230, 0xf1400, v228
	s_add_i32 m0, s46, 0x5000
	v_mfma_f32_16x16x32_bf16 v[86:89], v[140:143], v[216:219], v[86:89]
	global_load_lds_dwordx4 v230, s[40:41]
	v_add_u32_e32 v230, 0x121800, v228
	s_add_i32 m0, s46, 0x6000
	v_mfma_f32_16x16x32_bf16 v[92:95], v[144:147], v[216:219], v[92:95]
	global_load_lds_dwordx4 v230, s[40:41]
	v_add_u32_e32 v230, 0x151c00, v228
	s_add_i32 m0, s46, 0x7000
	v_mfma_f32_16x16x32_bf16 v[96:99], v[148:151], v[216:219], v[96:99]
	global_load_lds_dwordx4 v230, s[40:41]
	s_add_i32 m0, s46, 0x10000
	v_mfma_f32_16x16x32_bf16 v[100:103], v[136:139], v[220:223], v[100:103]
	global_load_lds_dwordx4 v237, s[42:43]
	v_add_u32_e32 v230, 0x4000, v237
	s_add_i32 m0, s46, 0x11000
	v_mfma_f32_16x16x32_bf16 v[104:107], v[140:143], v[220:223], v[104:107]
	global_load_lds_dwordx4 v230, s[42:43]
	v_add_u32_e32 v230, 0x8000, v237
	s_add_i32 m0, s46, 0x12000
	v_mfma_f32_16x16x32_bf16 v[108:111], v[144:147], v[220:223], v[108:111]
	global_load_lds_dwordx4 v230, s[42:43]
	v_add_u32_e32 v230, 0xc000, v237
	s_add_i32 m0, s46, 0x13000
	v_mfma_f32_16x16x32_bf16 v[112:115], v[148:151], v[220:223], v[112:115]
	global_load_lds_dwordx4 v230, s[42:43]
	v_mfma_f32_16x16x32_bf16 v[116:119], v[136:139], v[224:227], v[116:119]
	v_mfma_f32_16x16x32_bf16 v[120:123], v[140:143], v[224:227], v[120:123]
	v_mfma_f32_16x16x32_bf16 v[124:127], v[144:147], v[224:227], v[124:127]
	v_mfma_f32_16x16x32_bf16 v[128:131], v[148:151], v[224:227], v[128:131]
	ds_read_b128 v[212:215], v235 offset:40960
	ds_read_b128 v[216:219], v235 offset:43008
	ds_read_b128 v[220:223], v235 offset:45056
	ds_read_b128 v[224:227], v235 offset:47104
	s_waitcnt lgkmcnt(4)
	v_mfma_f32_16x16x32_bf16 v[2:5], v[152:155], v[196:199], v[2:5]
	v_mfma_f32_16x16x32_bf16 v[6:9], v[156:159], v[196:199], v[6:9]
	v_mfma_f32_16x16x32_bf16 v[10:13], v[160:163], v[196:199], v[10:13]
	v_mfma_f32_16x16x32_bf16 v[14:17], v[164:167], v[196:199], v[14:17]
	v_mfma_f32_16x16x32_bf16 v[18:21], v[152:155], v[200:203], v[18:21]
	v_mfma_f32_16x16x32_bf16 v[22:25], v[156:159], v[200:203], v[22:25]
	v_mfma_f32_16x16x32_bf16 v[26:29], v[160:163], v[200:203], v[26:29]
	v_mfma_f32_16x16x32_bf16 v[30:33], v[164:167], v[200:203], v[30:33]
	v_mfma_f32_16x16x32_bf16 v[34:37], v[152:155], v[204:207], v[34:37]
	v_mfma_f32_16x16x32_bf16 v[38:41], v[156:159], v[204:207], v[38:41]
	v_mfma_f32_16x16x32_bf16 v[42:45], v[160:163], v[204:207], v[42:45]
	v_mfma_f32_16x16x32_bf16 v[46:49], v[164:167], v[204:207], v[46:49]
	v_mfma_f32_16x16x32_bf16 v[50:53], v[152:155], v[208:211], v[50:53]
	v_mfma_f32_16x16x32_bf16 v[54:57], v[156:159], v[208:211], v[54:57]
	v_mfma_f32_16x16x32_bf16 v[58:61], v[160:163], v[208:211], v[58:61]
	v_mfma_f32_16x16x32_bf16 v[62:65], v[164:167], v[208:211], v[62:65]
	s_waitcnt lgkmcnt(0)
	v_mfma_f32_16x16x32_bf16 v[66:69], v[152:155], v[212:215], v[66:69]
	v_mfma_f32_16x16x32_bf16 v[70:73], v[156:159], v[212:215], v[70:73]
	v_mfma_f32_16x16x32_bf16 v[74:77], v[160:163], v[212:215], v[74:77]
	v_mfma_f32_16x16x32_bf16 v[78:81], v[164:167], v[212:215], v[78:81]
	v_mfma_f32_16x16x32_bf16 v[82:85], v[152:155], v[216:219], v[82:85]
	v_mfma_f32_16x16x32_bf16 v[86:89], v[156:159], v[216:219], v[86:89]
	v_mfma_f32_16x16x32_bf16 v[92:95], v[160:163], v[216:219], v[92:95]
	v_mfma_f32_16x16x32_bf16 v[96:99], v[164:167], v[216:219], v[96:99]
	v_mfma_f32_16x16x32_bf16 v[100:103], v[152:155], v[220:223], v[100:103]
	v_mfma_f32_16x16x32_bf16 v[104:107], v[156:159], v[220:223], v[104:107]
	v_mfma_f32_16x16x32_bf16 v[108:111], v[160:163], v[220:223], v[108:111]
	v_mfma_f32_16x16x32_bf16 v[112:115], v[164:167], v[220:223], v[112:115]
	v_mfma_f32_16x16x32_bf16 v[116:119], v[152:155], v[224:227], v[116:119]
	v_mfma_f32_16x16x32_bf16 v[120:123], v[156:159], v[224:227], v[120:123]
	v_mfma_f32_16x16x32_bf16 v[124:127], v[160:163], v[224:227], v[124:127]
	v_mfma_f32_16x16x32_bf16 v[128:131], v[164:167], v[224:227], v[128:131]
	s_setprio 0
	s_waitcnt vmcnt(0)
	s_barrier
;     ...
;   for (int kt = 0; kt < nk; ++kt) {
;     const int cur = (kt & 1) * 32768, nxt = 32768 - cur;
;     if (kt + 1 < nk) {
; #pragma unroll
;       for (int i = 0; i < 4; ++i)
;         __builtin_amdgcn_global_load_lds((const unsigned*)(A8 + (size_t)(kt + 1) * 128 + aoff[i]), (unsigned*)(smem + nxt + i * 4096 + wbase), 16, 0, 0);
; #pragma unroll
;       for (int i = 0; i < NT; ++i)
;         __builtin_amdgcn_global_load_lds((const unsigned*)(B8 + (size_t)(kt + 1) * 128 + boff[i]), (unsigned*)(smem + nxt + 16384 + i * 4096 + wbase), 16, 0, 0);
;     }
;     __builtin_amdgcn_sched_barrier(0);
;     if (LEAN) {
; #pragma unroll
;       for (int ks = 0; ks < 2; ++ks) {
;         bf16x8 af[4], bfr[NT];
; #pragma unroll
;         for (int m = 0; m < 4; ++m) af[m] = *(const bf16x8*)(smem + cur + ((abase + m * 2048) ^ (ks * 64)));
; #pragma unroll
;         for (int n = 0; n < NT; ++n) bfr[n] = *(const bf16x8*)(smem + cur + ((bbase + n * 2048) ^ (ks * 64)));
;         __builtin_amdgcn_s_setprio(1);
; #pragma unroll
;         for (int m = 0; m < 4; ++m)
; #pragma unroll
;           for (int n = 0; n < NT; ++n) acc[m][n] = __builtin_amdgcn_mfma_f32_16x16x32_bf16(bfr[n], af[m], acc[m][n], 0, 0, 0);
;         __builtin_amdgcn_s_setprio(0);
;       }
;     } else {
;     bf16x8 af0[4], bf0[NT], af1[4], bf1[NT];
; #pragma unroll
;     for (int m = 0; m < 4; ++m) af0[m] = *(const bf16x8*)(smem + cur + (abase + m * 2048));
; #pragma unroll
;     for (int n = 0; n < NT; ++n) bf0[n] = *(const bf16x8*)(smem + cur + (bbase + n * 2048));
; #pragma unroll
;     for (int m = 0; m < 4; ++m) af1[m] = *(const bf16x8*)(smem + cur + ((abase + m * 2048) ^ 64));
; #pragma unroll
;     for (int n = 0; n < NT; ++n) bf1[n] = *(const bf16x8*)(smem + cur + ((bbase + n * 2048) ^ 64));
;     __builtin_amdgcn_sched_barrier(0);
;     __builtin_amdgcn_s_setprio(1);
; #pragma unroll
;     for (int m = 0; m < 4; ++m)
; #pragma unroll
;       for (int n = 0; n < NT; ++n) acc[m][n] = __builtin_amdgcn_mfma_f32_16x16x32_bf16(bf0[n], af0[m], acc[m][n], 0, 0, 0);
; #pragma unroll
;     for (int m = 0; m < 4; ++m)
; #pragma unroll
;       for (int n = 0; n < NT; ++n) acc[m][n] = __builtin_amdgcn_mfma_f32_16x16x32_bf16(bf1[n], af1[m], acc[m][n], 0, 0, 0);
;     __builtin_amdgcn_s_setprio(0);
;     }
;     __builtin_amdgcn_sched_barrier(0);
;     asm volatile("s_waitcnt vmcnt(0)" ::: "memory");
	ds_read_b128 v[136:139], v232
	ds_read_b128 v[140:143], v232 offset:2048
	ds_read_b128 v[144:147], v232 offset:4096
	ds_read_b128 v[148:151], v232 offset:6144
	ds_read_b128 v[196:199], v231
	ds_read_b128 v[200:203], v231 offset:2048
	ds_read_b128 v[204:207], v231 offset:4096
	ds_read_b128 v[208:211], v231 offset:6144
	ds_read_b128 v[152:155], v236
	ds_read_b128 v[156:159], v236 offset:2048
	ds_read_b128 v[160:163], v236 offset:4096
	ds_read_b128 v[164:167], v236 offset:6144
	ds_read_b128 v[212:215], v231 offset:8192
	ds_read_b128 v[216:219], v231 offset:10240
	ds_read_b128 v[220:223], v231 offset:12288
	ds_read_b128 v[224:227], v231 offset:14336
	s_setprio 1
	s_waitcnt lgkmcnt(8)
	v_mfma_f32_16x16x32_bf16 v[2:5], v[136:139], v[196:199], v[2:5]
	v_mfma_f32_16x16x32_bf16 v[6:9], v[140:143], v[196:199], v[6:9]
	v_mfma_f32_16x16x32_bf16 v[10:13], v[144:147], v[196:199], v[10:13]
	v_mfma_f32_16x16x32_bf16 v[14:17], v[148:151], v[196:199], v[14:17]
	v_mfma_f32_16x16x32_bf16 v[18:21], v[136:139], v[200:203], v[18:21]
	v_mfma_f32_16x16x32_bf16 v[22:25], v[140:143], v[200:203], v[22:25]
	v_mfma_f32_16x16x32_bf16 v[26:29], v[144:147], v[200:203], v[26:29]
	v_mfma_f32_16x16x32_bf16 v[30:33], v[148:151], v[200:203], v[30:33]
	v_mfma_f32_16x16x32_bf16 v[34:37], v[136:139], v[204:207], v[34:37]
	v_mfma_f32_16x16x32_bf16 v[38:41], v[140:143], v[204:207], v[38:41]
	v_mfma_f32_16x16x32_bf16 v[42:45], v[144:147], v[204:207], v[42:45]
	v_mfma_f32_16x16x32_bf16 v[46:49], v[148:151], v[204:207], v[46:49]
	v_mfma_f32_16x16x32_bf16 v[50:53], v[136:139], v[208:211], v[50:53]
	v_mfma_f32_16x16x32_bf16 v[54:57], v[140:143], v[208:211], v[54:57]
	v_mfma_f32_16x16x32_bf16 v[58:61], v[144:147], v[208:211], v[58:61]
	v_mfma_f32_16x16x32_bf16 v[62:65], v[148:151], v[208:211], v[62:65]
	s_waitcnt lgkmcnt(0)
	s_barrier
	s_add_u32 s40, s40, 0x80
	s_addc_u32 s41, s41, 0
	s_add_u32 s42, s42, 0x80
	s_addc_u32 s43, s43, 0
	ds_read_b128 v[196:199], v235
	ds_read_b128 v[200:203], v235 offset:2048
	ds_read_b128 v[204:207], v235 offset:4096
	ds_read_b128 v[208:211], v235 offset:6144
	s_add_i32 m0, s46, 0x8000
	v_mfma_f32_16x16x32_bf16 v[66:69], v[136:139], v[212:215], v[66:69]
	global_load_lds_dwordx4 v228, s[40:41]
	v_add_u32_e32 v230, 0x30400, v228
	s_add_i32 m0, s46, 0x9000
	v_mfma_f32_16x16x32_bf16 v[70:73], v[140:143], v[212:215], v[70:73]
	global_load_lds_dwordx4 v230, s[40:41]
	v_add_u32_e32 v230, 0x60800, v228
	s_add_i32 m0, s46, 0xa000
	v_mfma_f32_16x16x32_bf16 v[74:77], v[144:147], v[212:215], v[74:77]
	global_load_lds_dwordx4 v230, s[40:41]
	v_add_u32_e32 v230, 0x90c00, v228
	s_add_i32 m0, s46, 0xb000
	v_mfma_f32_16x16x32_bf16 v[78:81], v[148:151], v[212:215], v[78:81]
	global_load_lds_dwordx4 v230, s[40:41]
	v_add_u32_e32 v230, 0xc1000, v228
	s_add_i32 m0, s46, 0xc000
	v_mfma_f32_16x16x32_bf16 v[82:85], v[136:139], v[216:219], v[82:85]
	global_load_lds_dwordx4 v230, s[40:41]
	v_add_u32_e32 v230, 0xf1400, v228
	s_add_i32 m0, s46, 0xd000
	v_mfma_f32_16x16x32_bf16 v[86:89], v[140:143], v[216:219], v[86:89]
	global_load_lds_dwordx4 v230, s[40:41]
	v_add_u32_e32 v230, 0x121800, v228
	s_add_i32 m0, s46, 0xe000
	v_mfma_f32_16x16x32_bf16 v[92:95], v[144:147], v[216:219], v[92:95]
	global_load_lds_dwordx4 v230, s[40:41]
	v_add_u32_e32 v230, 0x151c00, v228
	s_add_i32 m0, s46, 0xf000
	v_mfma_f32_16x16x32_bf16 v[96:99], v[148:151], v[216:219], v[96:99]
	global_load_lds_dwordx4 v230, s[40:41]
	s_add_i32 m0, s46, 0x10000
	v_mfma_f32_16x16x32_bf16 v[100:103], v[136:139], v[220:223], v[100:103]
	global_load_lds_dwordx4 v237, s[42:43]
	v_add_u32_e32 v230, 0x4000, v237
	s_add_i32 m0, s46, 0x11000
	v_mfma_f32_16x16x32_bf16 v[104:107], v[140:143], v[220:223], v[104:107]
	global_load_lds_dwordx4 v230, s[42:43]
	v_add_u32_e32 v230, 0x8000, v237
	s_add_i32 m0, s46, 0x12000
	v_mfma_f32_16x16x32_bf16 v[108:111], v[144:147], v[220:223], v[108:111]
	global_load_lds_dwordx4 v230, s[42:43]
	v_add_u32_e32 v230, 0xc000, v237
	s_add_i32 m0, s46, 0x13000
	v_mfma_f32_16x16x32_bf16 v[112:115], v[148:151], v[220:223], v[112:115]
	global_load_lds_dwordx4 v230, s[42:43]
	v_mfma_f32_16x16x32_bf16 v[116:119], v[136:139], v[224:227], v[116:119]
	v_mfma_f32_16x16x32_bf16 v[120:123], v[140:143], v[224:227], v[120:123]
	v_mfma_f32_16x16x32_bf16 v[124:127], v[144:147], v[224:227], v[124:127]
	v_mfma_f32_16x16x32_bf16 v[128:131], v[148:151], v[224:227], v[128:131]
	ds_read_b128 v[212:215], v235 offset:8192
	ds_read_b128 v[216:219], v235 offset:10240
	ds_read_b128 v[220:223], v235 offset:12288
	ds_read_b128 v[224:227], v235 offset:14336
	s_waitcnt lgkmcnt(4)
	v_mfma_f32_16x16x32_bf16 v[2:5], v[152:155], v[196:199], v[2:5]
	v_mfma_f32_16x16x32_bf16 v[6:9], v[156:159], v[196:199], v[6:9]
	v_mfma_f32_16x16x32_bf16 v[10:13], v[160:163], v[196:199], v[10:13]
	v_mfma_f32_16x16x32_bf16 v[14:17], v[164:167], v[196:199], v[14:17]
	v_mfma_f32_16x16x32_bf16 v[18:21], v[152:155], v[200:203], v[18:21]
	v_mfma_f32_16x16x32_bf16 v[22:25], v[156:159], v[200:203], v[22:25]
	v_mfma_f32_16x16x32_bf16 v[26:29], v[160:163], v[200:203], v[26:29]
	v_mfma_f32_16x16x32_bf16 v[30:33], v[164:167], v[200:203], v[30:33]
	v_mfma_f32_16x16x32_bf16 v[34:37], v[152:155], v[204:207], v[34:37]
	v_mfma_f32_16x16x32_bf16 v[38:41], v[156:159], v[204:207], v[38:41]
	v_mfma_f32_16x16x32_bf16 v[42:45], v[160:163], v[204:207], v[42:45]
	v_mfma_f32_16x16x32_bf16 v[46:49], v[164:167], v[204:207], v[46:49]
	v_mfma_f32_16x16x32_bf16 v[50:53], v[152:155], v[208:211], v[50:53]
	v_mfma_f32_16x16x32_bf16 v[54:57], v[156:159], v[208:211], v[54:57]
	v_mfma_f32_16x16x32_bf16 v[58:61], v[160:163], v[208:211], v[58:61]
	v_mfma_f32_16x16x32_bf16 v[62:65], v[164:167], v[208:211], v[62:65]
	s_waitcnt lgkmcnt(0)
	v_mfma_f32_16x16x32_bf16 v[66:69], v[152:155], v[212:215], v[66:69]
	v_mfma_f32_16x16x32_bf16 v[70:73], v[156:159], v[212:215], v[70:73]
	v_mfma_f32_16x16x32_bf16 v[74:77], v[160:163], v[212:215], v[74:77]
	v_mfma_f32_16x16x32_bf16 v[78:81], v[164:167], v[212:215], v[78:81]
	v_mfma_f32_16x16x32_bf16 v[82:85], v[152:155], v[216:219], v[82:85]
	v_mfma_f32_16x16x32_bf16 v[86:89], v[156:159], v[216:219], v[86:89]
	v_mfma_f32_16x16x32_bf16 v[92:95], v[160:163], v[216:219], v[92:95]
	v_mfma_f32_16x16x32_bf16 v[96:99], v[164:167], v[216:219], v[96:99]
	v_mfma_f32_16x16x32_bf16 v[100:103], v[152:155], v[220:223], v[100:103]
	v_mfma_f32_16x16x32_bf16 v[104:107], v[156:159], v[220:223], v[104:107]
	v_mfma_f32_16x16x32_bf16 v[108:111], v[160:163], v[220:223], v[108:111]
	v_mfma_f32_16x16x32_bf16 v[112:115], v[164:167], v[220:223], v[112:115]
	v_mfma_f32_16x16x32_bf16 v[116:119], v[152:155], v[224:227], v[116:119]
	v_mfma_f32_16x16x32_bf16 v[120:123], v[156:159], v[224:227], v[120:123]
	v_mfma_f32_16x16x32_bf16 v[124:127], v[160:163], v[224:227], v[124:127]
	v_mfma_f32_16x16x32_bf16 v[128:131], v[164:167], v[224:227], v[128:131]
	s_setprio 0
	s_waitcnt vmcnt(0)
	s_barrier
;     ...
;   for (int kt = 0; kt < nk; ++kt) {
;     const int cur = (kt & 1) * 32768, nxt = 32768 - cur;
;     if (kt + 1 < nk) {
; #pragma unroll
;       for (int i = 0; i < 4; ++i)
;         __builtin_amdgcn_global_load_lds((const unsigned*)(A8 + (size_t)(kt + 1) * 128 + aoff[i]), (unsigned*)(smem + nxt + i * 4096 + wbase), 16, 0, 0);
; #pragma unroll
;       for (int i = 0; i < NT; ++i)
;         __builtin_amdgcn_global_load_lds((const unsigned*)(B8 + (size_t)(kt + 1) * 128 + boff[i]), (unsigned*)(smem + nxt + 16384 + i * 4096 + wbase), 16, 0, 0);
;     }
;     __builtin_amdgcn_sched_barrier(0);
;     if (LEAN) {
; #pragma unroll
;       for (int ks = 0; ks < 2; ++ks) {
;         bf16x8 af[4], bfr[NT];
; #pragma unroll
;         for (int m = 0; m < 4; ++m) af[m] = *(const bf16x8*)(smem + cur + ((abase + m * 2048) ^ (ks * 64)));
; #pragma unroll
;         for (int n = 0; n < NT; ++n) bfr[n] = *(const bf16x8*)(smem + cur + ((bbase + n * 2048) ^ (ks * 64)));
;         __builtin_amdgcn_s_setprio(1);
; #pragma unroll
;         for (int m = 0; m < 4; ++m)
; #pragma unroll
;           for (int n = 0; n < NT; ++n) acc[m][n] = __builtin_amdgcn_mfma_f32_16x16x32_bf16(bfr[n], af[m], acc[m][n], 0, 0, 0);
;         __builtin_amdgcn_s_setprio(0);
;       }
;     } else {
;     bf16x8 af0[4], bf0[NT], af1[4], bf1[NT];
; #pragma unroll
;     for (int m = 0; m < 4; ++m) af0[m] = *(const bf16x8*)(smem + cur + (abase + m * 2048));
; #pragma unroll
;     for (int n = 0; n < NT; ++n) bf0[n] = *(const bf16x8*)(smem + cur + (bbase + n * 2048));
; #pragma unroll
;     for (int m = 0; m < 4; ++m) af1[m] = *(const bf16x8*)(smem + cur + ((abase + m * 2048) ^ 64));
; #pragma unroll
;     for (int n = 0; n < NT; ++n) bf1[n] = *(const bf16x8*)(smem + cur + ((bbase + n * 2048) ^ 64));
;     __builtin_amdgcn_sched_barrier(0);
;     __builtin_amdgcn_s_setprio(1);
; #pragma unroll
;     for (int m = 0; m < 4; ++m)
; #pragma unroll
;       for (int n = 0; n < NT; ++n) acc[m][n] = __builtin_amdgcn_mfma_f32_16x16x32_bf16(bf0[n], af0[m], acc[m][n], 0, 0, 0);
; #pragma unroll
;     for (int m = 0; m < 4; ++m)
; #pragma unroll
;       for (int n = 0; n < NT; ++n) acc[m][n] = __builtin_amdgcn_mfma_f32_16x16x32_bf16(bf1[n], af1[m], acc[m][n], 0, 0, 0);
;     __builtin_amdgcn_s_setprio(0);
;     }
;     __builtin_amdgcn_sched_barrier(0);
;     asm volatile("s_waitcnt vmcnt(0)" ::: "memory");
	ds_read_b128 v[136:139], v232
	ds_read_b128 v[140:143], v232 offset:2048
	ds_read_b128 v[144:147], v232 offset:4096
	ds_read_b128 v[148:151], v232 offset:6144
	ds_read_b128 v[196:199], v231 offset:32768
	ds_read_b128 v[200:203], v231 offset:34816
	ds_read_b128 v[204:207], v231 offset:36864
	ds_read_b128 v[208:211], v231 offset:38912
	ds_read_b128 v[152:155], v236
	ds_read_b128 v[156:159], v236 offset:2048
	ds_read_b128 v[160:163], v236 offset:4096
	ds_read_b128 v[164:167], v236 offset:6144
	ds_read_b128 v[212:215], v231 offset:40960
	ds_read_b128 v[216:219], v231 offset:43008
	ds_read_b128 v[220:223], v231 offset:45056
	ds_read_b128 v[224:227], v231 offset:47104
	s_setprio 1
	s_waitcnt lgkmcnt(8)
	v_mfma_f32_16x16x32_bf16 v[2:5], v[136:139], v[196:199], v[2:5]
	v_mfma_f32_16x16x32_bf16 v[6:9], v[140:143], v[196:199], v[6:9]
	v_mfma_f32_16x16x32_bf16 v[10:13], v[144:147], v[196:199], v[10:13]
	v_mfma_f32_16x16x32_bf16 v[14:17], v[148:151], v[196:199], v[14:17]
	v_mfma_f32_16x16x32_bf16 v[18:21], v[136:139], v[200:203], v[18:21]
	v_mfma_f32_16x16x32_bf16 v[22:25], v[140:143], v[200:203], v[22:25]
	v_mfma_f32_16x16x32_bf16 v[26:29], v[144:147], v[200:203], v[26:29]
	v_mfma_f32_16x16x32_bf16 v[30:33], v[148:151], v[200:203], v[30:33]
	v_mfma_f32_16x16x32_bf16 v[34:37], v[136:139], v[204:207], v[34:37]
	v_mfma_f32_16x16x32_bf16 v[38:41], v[140:143], v[204:207], v[38:41]
	v_mfma_f32_16x16x32_bf16 v[42:45], v[144:147], v[204:207], v[42:45]
	v_mfma_f32_16x16x32_bf16 v[46:49], v[148:151], v[204:207], v[46:49]
	v_mfma_f32_16x16x32_bf16 v[50:53], v[136:139], v[208:211], v[50:53]
	v_mfma_f32_16x16x32_bf16 v[54:57], v[140:143], v[208:211], v[54:57]
	v_mfma_f32_16x16x32_bf16 v[58:61], v[144:147], v[208:211], v[58:61]
	v_mfma_f32_16x16x32_bf16 v[62:65], v[148:151], v[208:211], v[62:65]
	s_waitcnt lgkmcnt(0)
	ds_read_b128 v[196:199], v235 offset:32768
	ds_read_b128 v[200:203], v235 offset:34816
	ds_read_b128 v[204:207], v235 offset:36864
	ds_read_b128 v[208:211], v235 offset:38912
	v_mfma_f32_16x16x32_bf16 v[66:69], v[136:139], v[212:215], v[66:69]
	v_mfma_f32_16x16x32_bf16 v[70:73], v[140:143], v[212:215], v[70:73]
	v_mfma_f32_16x16x32_bf16 v[74:77], v[144:147], v[212:215], v[74:77]
	v_mfma_f32_16x16x32_bf16 v[78:81], v[148:151], v[212:215], v[78:81]
	v_mfma_f32_16x16x32_bf16 v[82:85], v[136:139], v[216:219], v[82:85]
	v_mfma_f32_16x16x32_bf16 v[86:89], v[140:143], v[216:219], v[86:89]
	v_mfma_f32_16x16x32_bf16 v[92:95], v[144:147], v[216:219], v[92:95]
	v_mfma_f32_16x16x32_bf16 v[96:99], v[148:151], v[216:219], v[96:99]
	v_mfma_f32_16x16x32_bf16 v[100:103], v[136:139], v[220:223], v[100:103]
	v_mfma_f32_16x16x32_bf16 v[104:107], v[140:143], v[220:223], v[104:107]
	v_mfma_f32_16x16x32_bf16 v[108:111], v[144:147], v[220:223], v[108:111]
	v_mfma_f32_16x16x32_bf16 v[112:115], v[148:151], v[220:223], v[112:115]
	v_mfma_f32_16x16x32_bf16 v[116:119], v[136:139], v[224:227], v[116:119]
	v_mfma_f32_16x16x32_bf16 v[120:123], v[140:143], v[224:227], v[120:123]
	v_mfma_f32_16x16x32_bf16 v[124:127], v[144:147], v[224:227], v[124:127]
	v_mfma_f32_16x16x32_bf16 v[128:131], v[148:151], v[224:227], v[128:131]
	ds_read_b128 v[212:215], v235 offset:40960
	ds_read_b128 v[216:219], v235 offset:43008
	ds_read_b128 v[220:223], v235 offset:45056
	ds_read_b128 v[224:227], v235 offset:47104
	s_waitcnt lgkmcnt(4)
	v_mfma_f32_16x16x32_bf16 v[2:5], v[152:155], v[196:199], v[2:5]
	v_mfma_f32_16x16x32_bf16 v[6:9], v[156:159], v[196:199], v[6:9]
	v_mfma_f32_16x16x32_bf16 v[10:13], v[160:163], v[196:199], v[10:13]
	v_mfma_f32_16x16x32_bf16 v[14:17], v[164:167], v[196:199], v[14:17]
	v_mfma_f32_16x16x32_bf16 v[18:21], v[152:155], v[200:203], v[18:21]
	v_mfma_f32_16x16x32_bf16 v[22:25], v[156:159], v[200:203], v[22:25]
	v_mfma_f32_16x16x32_bf16 v[26:29], v[160:163], v[200:203], v[26:29]
	v_mfma_f32_16x16x32_bf16 v[30:33], v[164:167], v[200:203], v[30:33]
	v_mfma_f32_16x16x32_bf16 v[34:37], v[152:155], v[204:207], v[34:37]
	v_mfma_f32_16x16x32_bf16 v[38:41], v[156:159], v[204:207], v[38:41]
	v_mfma_f32_16x16x32_bf16 v[42:45], v[160:163], v[204:207], v[42:45]
	v_mfma_f32_16x16x32_bf16 v[46:49], v[164:167], v[204:207], v[46:49]
	v_mfma_f32_16x16x32_bf16 v[50:53], v[152:155], v[208:211], v[50:53]
	v_mfma_f32_16x16x32_bf16 v[54:57], v[156:159], v[208:211], v[54:57]
	v_mfma_f32_16x16x32_bf16 v[58:61], v[160:163], v[208:211], v[58:61]
	v_mfma_f32_16x16x32_bf16 v[62:65], v[164:167], v[208:211], v[62:65]
	s_waitcnt lgkmcnt(0)
	v_mfma_f32_16x16x32_bf16 v[66:69], v[152:155], v[212:215], v[66:69]
	v_mfma_f32_16x16x32_bf16 v[70:73], v[156:159], v[212:215], v[70:73]
	v_mfma_f32_16x16x32_bf16 v[74:77], v[160:163], v[212:215], v[74:77]
	v_mfma_f32_16x16x32_bf16 v[78:81], v[164:167], v[212:215], v[78:81]
	v_mfma_f32_16x16x32_bf16 v[82:85], v[152:155], v[216:219], v[82:85]
	v_mfma_f32_16x16x32_bf16 v[86:89], v[156:159], v[216:219], v[86:89]
	v_mfma_f32_16x16x32_bf16 v[92:95], v[160:163], v[216:219], v[92:95]
	v_mfma_f32_16x16x32_bf16 v[96:99], v[164:167], v[216:219], v[96:99]
	v_mfma_f32_16x16x32_bf16 v[100:103], v[152:155], v[220:223], v[100:103]
	v_mfma_f32_16x16x32_bf16 v[104:107], v[156:159], v[220:223], v[104:107]
	v_mfma_f32_16x16x32_bf16 v[108:111], v[160:163], v[220:223], v[108:111]
	v_mfma_f32_16x16x32_bf16 v[112:115], v[164:167], v[220:223], v[112:115]
	v_mfma_f32_16x16x32_bf16 v[116:119], v[152:155], v[224:227], v[116:119]
	v_mfma_f32_16x16x32_bf16 v[120:123], v[156:159], v[224:227], v[120:123]
	v_mfma_f32_16x16x32_bf16 v[124:127], v[160:163], v[224:227], v[124:127]
	v_mfma_f32_16x16x32_bf16 v[128:131], v[164:167], v[224:227], v[128:131]
	s_setprio 0
	s_waitcnt vmcnt(0)
	s_barrier
	s_and_saveexec_b64 s[48:49], s[62:63]
	s_cbranch_execz .Lgl_tk1
	v_add_u32_e32 v0, s73, v233
	ds_write_b32 v1, v0
; __device__ __forceinline__ float sigm(float x) { return __builtin_amdgcn_rcpf(1.f + __expf(-x)); }
;   __device__ __forceinline__ void next(char* smem) {
;     if (!cnt) { e += nb; return; }
;     if (threadIdx.x == 0) *(volatile int*)smem = (int)tick + nb;
;     __syncthreads();
;     e = *(volatile int*)smem;
;     __syncthreads();
;   }
; __device__ __forceinline__ void phase_glu(const Params& p, int mrows, char* smem) {
;     ...
;     bf16_t* ob = P + (size_t)(tm * 128 + wr * 64 + fr) * PC + C_YS5 + tn * 64 + wc * 32 + fq * 4;
; #pragma unroll
;     for (int m = 0; m < 4; ++m) {
; #pragma unroll
;       for (int np = 0; np < 2; ++np) {
;         float o[4];
; #pragma unroll
;         for (int j = 0; j < 4; ++j) o[j] = acc[m][2 * np][j] * sigm(acc[m][2 * np + 1][j]);
;         u32x2 pk; pk.x = pack2(o[0], o[1]); pk.y = pack2(o[2], o[3]);
;         *(u32x2*)(ob + (m * 16) * PC + np * 16) = pk;
;       }
;       __builtin_amdgcn_sched_barrier(0);
;     }
.Lgl_tk1:
	s_or_b64 exec, exec, s[48:49]
	s_waitcnt lgkmcnt(0)
	s_barrier
	ds_read_b32 v0, v1
	s_waitcnt lgkmcnt(0)
	v_readfirstlane_b32 s44, v0
	s_barrier
	s_mul_i32 s45, s47, 0x182000
	s_mul_hi_u32 s48, s47, 0x182000
	s_add_u32 s50, s100, s45
	s_addc_u32 s51, s101, s48
	s_add_u32 s50, s50, 0x8b80400
	s_addc_u32 s51, s51, 0
	s_lshl_b32 s45, s98, 7
	s_add_u32 s50, s50, s45
	s_addc_u32 s51, s51, 0
	v_mul_f32_e32 v238, 0xbfb8aa3b, v6
	v_mul_f32_e32 v239, 0xbfb8aa3b, v7
	v_mul_f32_e32 v240, 0xbfb8aa3b, v8
	v_mul_f32_e32 v241, 0xbfb8aa3b, v9
	v_exp_f32_e32 v238, v238
	v_exp_f32_e32 v239, v239
	v_exp_f32_e32 v240, v240
	v_exp_f32_e32 v241, v241
	v_add_f32_e32 v238, 1.0, v238
	v_add_f32_e32 v239, 1.0, v239
	v_add_f32_e32 v240, 1.0, v240
	v_add_f32_e32 v241, 1.0, v241
	v_rcp_f32_e32 v238, v238
	v_rcp_f32_e32 v239, v239
	v_rcp_f32_e32 v240, v240
	v_rcp_f32_e32 v241, v241
	v_mul_f32_e32 v2, v2, v238
	v_mul_f32_e32 v3, v3, v239
	v_mul_f32_e32 v4, v4, v240
	v_mul_f32_e32 v5, v5, v241
	v_cvt_pk_bf16_f32 v2, v2, v3
	v_cvt_pk_bf16_f32 v3, v4, v5
	global_store_dwordx2 v234, v[2:3], s[50:51]
	v_mul_f32_e32 v238, 0xbfb8aa3b, v14
	v_mul_f32_e32 v239, 0xbfb8aa3b, v15
	v_mul_f32_e32 v240, 0xbfb8aa3b, v16
	v_mul_f32_e32 v241, 0xbfb8aa3b, v17
	v_exp_f32_e32 v238, v238
	v_exp_f32_e32 v239, v239
	v_exp_f32_e32 v240, v240
	v_exp_f32_e32 v241, v241
	v_add_f32_e32 v238, 1.0, v238
	v_add_f32_e32 v239, 1.0, v239
	v_add_f32_e32 v240, 1.0, v240
	v_add_f32_e32 v241, 1.0, v241
	v_rcp_f32_e32 v238, v238
	v_rcp_f32_e32 v239, v239
	v_rcp_f32_e32 v240, v240
	v_rcp_f32_e32 v241, v241
	v_mul_f32_e32 v10, v10, v238
	v_mul_f32_e32 v11, v11, v239
	v_mul_f32_e32 v12, v12, v240
	v_mul_f32_e32 v13, v13, v241
	v_cvt_pk_bf16_f32 v10, v10, v11
	v_cvt_pk_bf16_f32 v11, v12, v13
	global_store_dwordx2 v234, v[10:11], s[50:51] offset:32
	s_add_u32 s50, s50, 0x18200
	s_addc_u32 s51, s51, 0
	v_mul_f32_e32 v238, 0xbfb8aa3b, v22
	v_mul_f32_e32 v239, 0xbfb8aa3b, v23
	v_mul_f32_e32 v240, 0xbfb8aa3b, v24
	v_mul_f32_e32 v241, 0xbfb8aa3b, v25
	v_exp_f32_e32 v238, v238
	v_exp_f32_e32 v239, v239
	v_exp_f32_e32 v240, v240
	v_exp_f32_e32 v241, v241
	v_add_f32_e32 v238, 1.0, v238
	v_add_f32_e32 v239, 1.0, v239
	v_add_f32_e32 v240, 1.0, v240
	v_add_f32_e32 v241, 1.0, v241
	v_rcp_f32_e32 v238, v238
	v_rcp_f32_e32 v239, v239
	v_rcp_f32_e32 v240, v240
	v_rcp_f32_e32 v241, v241
	v_mul_f32_e32 v18, v18, v238
	v_mul_f32_e32 v19, v19, v239
	v_mul_f32_e32 v20, v20, v240
	v_mul_f32_e32 v21, v21, v241
	v_cvt_pk_bf16_f32 v18, v18, v19
	v_cvt_pk_bf16_f32 v19, v20, v21
	global_store_dwordx2 v234, v[18:19], s[50:51]
	v_mul_f32_e32 v238, 0xbfb8aa3b, v30
	v_mul_f32_e32 v239, 0xbfb8aa3b, v31
	v_mul_f32_e32 v240, 0xbfb8aa3b, v32
	v_mul_f32_e32 v241, 0xbfb8aa3b, v33
	v_exp_f32_e32 v238, v238
	v_exp_f32_e32 v239, v239
	v_exp_f32_e32 v240, v240
	v_exp_f32_e32 v241, v241
	v_add_f32_e32 v238, 1.0, v238
	v_add_f32_e32 v239, 1.0, v239
	v_add_f32_e32 v240, 1.0, v240
	v_add_f32_e32 v241, 1.0, v241
	v_rcp_f32_e32 v238, v238
	v_rcp_f32_e32 v239, v239
	v_rcp_f32_e32 v240, v240
	v_rcp_f32_e32 v241, v241
	v_mul_f32_e32 v26, v26, v238
	v_mul_f32_e32 v27, v27, v239
	v_mul_f32_e32 v28, v28, v240
	v_mul_f32_e32 v29, v29, v241
	v_cvt_pk_bf16_f32 v26, v26, v27
	v_cvt_pk_bf16_f32 v27, v28, v29
	global_store_dwordx2 v234, v[26:27], s[50:51] offset:32
	s_add_u32 s50, s50, 0x18200
	s_addc_u32 s51, s51, 0
	v_mul_f32_e32 v238, 0xbfb8aa3b, v38
	v_mul_f32_e32 v239, 0xbfb8aa3b, v39
	v_mul_f32_e32 v240, 0xbfb8aa3b, v40
	v_mul_f32_e32 v241, 0xbfb8aa3b, v41
	v_exp_f32_e32 v238, v238
	v_exp_f32_e32 v239, v239
	v_exp_f32_e32 v240, v240
	v_exp_f32_e32 v241, v241
	v_add_f32_e32 v238, 1.0, v238
	v_add_f32_e32 v239, 1.0, v239
	v_add_f32_e32 v240, 1.0, v240
	v_add_f32_e32 v241, 1.0, v241
	v_rcp_f32_e32 v238, v238
	v_rcp_f32_e32 v239, v239
	v_rcp_f32_e32 v240, v240
	v_rcp_f32_e32 v241, v241
	v_mul_f32_e32 v34, v34, v238
	v_mul_f32_e32 v35, v35, v239
	v_mul_f32_e32 v36, v36, v240
	v_mul_f32_e32 v37, v37, v241
	v_cvt_pk_bf16_f32 v34, v34, v35
	v_cvt_pk_bf16_f32 v35, v36, v37
	global_store_dwordx2 v234, v[34:35], s[50:51]
	v_mul_f32_e32 v238, 0xbfb8aa3b, v46
	v_mul_f32_e32 v239, 0xbfb8aa3b, v47
	v_mul_f32_e32 v240, 0xbfb8aa3b, v48
	v_mul_f32_e32 v241, 0xbfb8aa3b, v49
	v_exp_f32_e32 v238, v238
	v_exp_f32_e32 v239, v239
	v_exp_f32_e32 v240, v240
	v_exp_f32_e32 v241, v241
	v_add_f32_e32 v238, 1.0, v238
	v_add_f32_e32 v239, 1.0, v239
	v_add_f32_e32 v240, 1.0, v240
	v_add_f32_e32 v241, 1.0, v241
	v_rcp_f32_e32 v238, v238
	v_rcp_f32_e32 v239, v239
	v_rcp_f32_e32 v240, v240
	v_rcp_f32_e32 v241, v241
	v_mul_f32_e32 v42, v42, v238
	v_mul_f32_e32 v43, v43, v239
	v_mul_f32_e32 v44, v44, v240
	v_mul_f32_e32 v45, v45, v241
	v_cvt_pk_bf16_f32 v42, v42, v43
	v_cvt_pk_bf16_f32 v43, v44, v45
	global_store_dwordx2 v234, v[42:43], s[50:51] offset:32
	s_add_u32 s50, s50, 0x18200
	s_addc_u32 s51, s51, 0
	v_mul_f32_e32 v238, 0xbfb8aa3b, v54
	v_mul_f32_e32 v239, 0xbfb8aa3b, v55
	v_mul_f32_e32 v240, 0xbfb8aa3b, v56
	v_mul_f32_e32 v241, 0xbfb8aa3b, v57
	v_exp_f32_e32 v238, v238
	v_exp_f32_e32 v239, v239
	v_exp_f32_e32 v240, v240
	v_exp_f32_e32 v241, v241
	v_add_f32_e32 v238, 1.0, v238
	v_add_f32_e32 v239, 1.0, v239
	v_add_f32_e32 v240, 1.0, v240
	v_add_f32_e32 v241, 1.0, v241
	v_rcp_f32_e32 v238, v238
	v_rcp_f32_e32 v239, v239
	v_rcp_f32_e32 v240, v240
	v_rcp_f32_e32 v241, v241
	v_mul_f32_e32 v50, v50, v238
	v_mul_f32_e32 v51, v51, v239
	v_mul_f32_e32 v52, v52, v240
	v_mul_f32_e32 v53, v53, v241
	v_cvt_pk_bf16_f32 v50, v50, v51
	v_cvt_pk_bf16_f32 v51, v52, v53
	global_store_dwordx2 v234, v[50:51], s[50:51]
	v_mul_f32_e32 v238, 0xbfb8aa3b, v62
	v_mul_f32_e32 v239, 0xbfb8aa3b, v63
; __device__ __forceinline__ float sigm(float x) { return __builtin_amdgcn_rcpf(1.f + __expf(-x)); }
; __device__ __forceinline__ void phase_glu(const Params& p, int mrows, char* smem) {
;     ...
;     bf16_t* ob = P + (size_t)(tm * 128 + wr * 64 + fr) * PC + C_YS5 + tn * 64 + wc * 32 + fq * 4;
; #pragma unroll
;     for (int m = 0; m < 4; ++m) {
; #pragma unroll
;       for (int np = 0; np < 2; ++np) {
;         float o[4];
; #pragma unroll
;         for (int j = 0; j < 4; ++j) o[j] = acc[m][2 * np][j] * sigm(acc[m][2 * np + 1][j]);
;         u32x2 pk; pk.x = pack2(o[0], o[1]); pk.y = pack2(o[2], o[3]);
;         *(u32x2*)(ob + (m * 16) * PC + np * 16) = pk;
;       }
;       __builtin_amdgcn_sched_barrier(0);
;     }
	v_mul_f32_e32 v240, 0xbfb8aa3b, v64
	v_mul_f32_e32 v241, 0xbfb8aa3b, v65
	v_exp_f32_e32 v238, v238
	v_exp_f32_e32 v239, v239
	v_exp_f32_e32 v240, v240
	v_exp_f32_e32 v241, v241
	v_add_f32_e32 v238, 1.0, v238
	v_add_f32_e32 v239, 1.0, v239
	v_add_f32_e32 v240, 1.0, v240
	v_add_f32_e32 v241, 1.0, v241
	v_rcp_f32_e32 v238, v238
	v_rcp_f32_e32 v239, v239
	v_rcp_f32_e32 v240, v240
	v_rcp_f32_e32 v241, v241
	v_mul_f32_e32 v58, v58, v238
	v_mul_f32_e32 v59, v59, v239
	v_mul_f32_e32 v60, v60, v240
	v_mul_f32_e32 v61, v61, v241
	v_cvt_pk_bf16_f32 v58, v58, v59
	v_cvt_pk_bf16_f32 v59, v60, v61
	global_store_dwordx2 v234, v[58:59], s[50:51] offset:32
	s_add_u32 s50, s50, 0x18200
	s_addc_u32 s51, s51, 0
	v_mul_f32_e32 v238, 0xbfb8aa3b, v70
	v_mul_f32_e32 v239, 0xbfb8aa3b, v71
	v_mul_f32_e32 v240, 0xbfb8aa3b, v72
	v_mul_f32_e32 v241, 0xbfb8aa3b, v73
	v_exp_f32_e32 v238, v238
	v_exp_f32_e32 v239, v239
	v_exp_f32_e32 v240, v240
	v_exp_f32_e32 v241, v241
	v_add_f32_e32 v238, 1.0, v238
	v_add_f32_e32 v239, 1.0, v239
	v_add_f32_e32 v240, 1.0, v240
	v_add_f32_e32 v241, 1.0, v241
	v_rcp_f32_e32 v238, v238
	v_rcp_f32_e32 v239, v239
	v_rcp_f32_e32 v240, v240
	v_rcp_f32_e32 v241, v241
	v_mul_f32_e32 v66, v66, v238
	v_mul_f32_e32 v67, v67, v239
	v_mul_f32_e32 v68, v68, v240
	v_mul_f32_e32 v69, v69, v241
	v_cvt_pk_bf16_f32 v66, v66, v67
	v_cvt_pk_bf16_f32 v67, v68, v69
	global_store_dwordx2 v234, v[66:67], s[50:51]
	v_mul_f32_e32 v238, 0xbfb8aa3b, v78
	v_mul_f32_e32 v239, 0xbfb8aa3b, v79
	v_mul_f32_e32 v240, 0xbfb8aa3b, v80
	v_mul_f32_e32 v241, 0xbfb8aa3b, v81
	v_exp_f32_e32 v238, v238
	v_exp_f32_e32 v239, v239
	v_exp_f32_e32 v240, v240
	v_exp_f32_e32 v241, v241
	v_add_f32_e32 v238, 1.0, v238
	v_add_f32_e32 v239, 1.0, v239
	v_add_f32_e32 v240, 1.0, v240
	v_add_f32_e32 v241, 1.0, v241
	v_rcp_f32_e32 v238, v238
	v_rcp_f32_e32 v239, v239
	v_rcp_f32_e32 v240, v240
	v_rcp_f32_e32 v241, v241
	v_mul_f32_e32 v74, v74, v238
	v_mul_f32_e32 v75, v75, v239
	v_mul_f32_e32 v76, v76, v240
	v_mul_f32_e32 v77, v77, v241
	v_cvt_pk_bf16_f32 v74, v74, v75
	v_cvt_pk_bf16_f32 v75, v76, v77
	global_store_dwordx2 v234, v[74:75], s[50:51] offset:32
	s_add_u32 s50, s50, 0x18200
	s_addc_u32 s51, s51, 0
	v_mul_f32_e32 v238, 0xbfb8aa3b, v86
	v_mul_f32_e32 v239, 0xbfb8aa3b, v87
	v_mul_f32_e32 v240, 0xbfb8aa3b, v88
	v_mul_f32_e32 v241, 0xbfb8aa3b, v89
	v_exp_f32_e32 v238, v238
	v_exp_f32_e32 v239, v239
	v_exp_f32_e32 v240, v240
	v_exp_f32_e32 v241, v241
	v_add_f32_e32 v238, 1.0, v238
	v_add_f32_e32 v239, 1.0, v239
	v_add_f32_e32 v240, 1.0, v240
	v_add_f32_e32 v241, 1.0, v241
	v_rcp_f32_e32 v238, v238
	v_rcp_f32_e32 v239, v239
	v_rcp_f32_e32 v240, v240
	v_rcp_f32_e32 v241, v241
	v_mul_f32_e32 v82, v82, v238
	v_mul_f32_e32 v83, v83, v239
	v_mul_f32_e32 v84, v84, v240
	v_mul_f32_e32 v85, v85, v241
	v_cvt_pk_bf16_f32 v82, v82, v83
	v_cvt_pk_bf16_f32 v83, v84, v85
	global_store_dwordx2 v234, v[82:83], s[50:51]
	v_mul_f32_e32 v238, 0xbfb8aa3b, v96
	v_mul_f32_e32 v239, 0xbfb8aa3b, v97
	v_mul_f32_e32 v240, 0xbfb8aa3b, v98
	v_mul_f32_e32 v241, 0xbfb8aa3b, v99
	v_exp_f32_e32 v238, v238
	v_exp_f32_e32 v239, v239
	v_exp_f32_e32 v240, v240
	v_exp_f32_e32 v241, v241
	v_add_f32_e32 v238, 1.0, v238
	v_add_f32_e32 v239, 1.0, v239
	v_add_f32_e32 v240, 1.0, v240
	v_add_f32_e32 v241, 1.0, v241
	v_rcp_f32_e32 v238, v238
	v_rcp_f32_e32 v239, v239
	v_rcp_f32_e32 v240, v240
	v_rcp_f32_e32 v241, v241
	v_mul_f32_e32 v92, v92, v238
	v_mul_f32_e32 v93, v93, v239
	v_mul_f32_e32 v94, v94, v240
	v_mul_f32_e32 v95, v95, v241
	v_cvt_pk_bf16_f32 v92, v92, v93
	v_cvt_pk_bf16_f32 v93, v94, v95
	global_store_dwordx2 v234, v[92:93], s[50:51] offset:32
	s_add_u32 s50, s50, 0x18200
	s_addc_u32 s51, s51, 0
	v_mul_f32_e32 v238, 0xbfb8aa3b, v104
	v_mul_f32_e32 v239, 0xbfb8aa3b, v105
	v_mul_f32_e32 v240, 0xbfb8aa3b, v106
	v_mul_f32_e32 v241, 0xbfb8aa3b, v107
	v_exp_f32_e32 v238, v238
	v_exp_f32_e32 v239, v239
	v_exp_f32_e32 v240, v240
	v_exp_f32_e32 v241, v241
	v_add_f32_e32 v238, 1.0, v238
	v_add_f32_e32 v239, 1.0, v239
	v_add_f32_e32 v240, 1.0, v240
	v_add_f32_e32 v241, 1.0, v241
	v_rcp_f32_e32 v238, v238
	v_rcp_f32_e32 v239, v239
	v_rcp_f32_e32 v240, v240
	v_rcp_f32_e32 v241, v241
	v_mul_f32_e32 v100, v100, v238
	v_mul_f32_e32 v101, v101, v239
	v_mul_f32_e32 v102, v102, v240
	v_mul_f32_e32 v103, v103, v241
	v_cvt_pk_bf16_f32 v100, v100, v101
	v_cvt_pk_bf16_f32 v101, v102, v103
	global_store_dwordx2 v234, v[100:101], s[50:51]
	v_mul_f32_e32 v238, 0xbfb8aa3b, v112
	v_mul_f32_e32 v239, 0xbfb8aa3b, v113
	v_mul_f32_e32 v240, 0xbfb8aa3b, v114
	v_mul_f32_e32 v241, 0xbfb8aa3b, v115
	v_exp_f32_e32 v238, v238
	v_exp_f32_e32 v239, v239
	v_exp_f32_e32 v240, v240
	v_exp_f32_e32 v241, v241
	v_add_f32_e32 v238, 1.0, v238
	v_add_f32_e32 v239, 1.0, v239
	v_add_f32_e32 v240, 1.0, v240
	v_add_f32_e32 v241, 1.0, v241
	v_rcp_f32_e32 v238, v238
	v_rcp_f32_e32 v239, v239
	v_rcp_f32_e32 v240, v240
	v_rcp_f32_e32 v241, v241
	v_mul_f32_e32 v108, v108, v238
	v_mul_f32_e32 v109, v109, v239
	v_mul_f32_e32 v110, v110, v240
	v_mul_f32_e32 v111, v111, v241
	v_cvt_pk_bf16_f32 v108, v108, v109
	v_cvt_pk_bf16_f32 v109, v110, v111
	global_store_dwordx2 v234, v[108:109], s[50:51] offset:32
	s_add_u32 s50, s50, 0x18200
	s_addc_u32 s51, s51, 0
	v_mul_f32_e32 v238, 0xbfb8aa3b, v120
	v_mul_f32_e32 v239, 0xbfb8aa3b, v121
	v_mul_f32_e32 v240, 0xbfb8aa3b, v122
	v_mul_f32_e32 v241, 0xbfb8aa3b, v123
	v_exp_f32_e32 v238, v238
	v_exp_f32_e32 v239, v239
	v_exp_f32_e32 v240, v240
	v_exp_f32_e32 v241, v241
	v_add_f32_e32 v238, 1.0, v238
	v_add_f32_e32 v239, 1.0, v239
	v_add_f32_e32 v240, 1.0, v240
	v_add_f32_e32 v241, 1.0, v241
	v_rcp_f32_e32 v238, v238
	v_rcp_f32_e32 v239, v239
	v_rcp_f32_e32 v240, v240
	v_rcp_f32_e32 v241, v241
	v_mul_f32_e32 v116, v116, v238
	v_mul_f32_e32 v117, v117, v239
	v_mul_f32_e32 v118, v118, v240
	v_mul_f32_e32 v119, v119, v241
	v_cvt_pk_bf16_f32 v116, v116, v117
	v_cvt_pk_bf16_f32 v117, v118, v119
	global_store_dwordx2 v234, v[116:117], s[50:51]
	v_mul_f32_e32 v238, 0xbfb8aa3b, v128
	v_mul_f32_e32 v239, 0xbfb8aa3b, v129
	v_mul_f32_e32 v240, 0xbfb8aa3b, v130
	v_mul_f32_e32 v241, 0xbfb8aa3b, v131
	v_exp_f32_e32 v238, v238
	v_exp_f32_e32 v239, v239
	v_exp_f32_e32 v240, v240
	v_exp_f32_e32 v241, v241
	v_add_f32_e32 v238, 1.0, v238
	v_add_f32_e32 v239, 1.0, v239
	v_add_f32_e32 v240, 1.0, v240
	v_add_f32_e32 v241, 1.0, v241
	v_rcp_f32_e32 v238, v238
	v_rcp_f32_e32 v239, v239
	v_rcp_f32_e32 v240, v240
	v_rcp_f32_e32 v241, v241
	v_mul_f32_e32 v124, v124, v238
	v_mul_f32_e32 v125, v125, v239
	v_mul_f32_e32 v126, v126, v240
	v_mul_f32_e32 v127, v127, v241
	v_cvt_pk_bf16_f32 v124, v124, v125
	v_cvt_pk_bf16_f32 v125, v126, v127
	global_store_dwordx2 v234, v[124:125], s[50:51] offset:32
	s_branch .Lgl_tile
; __device__ __forceinline__ void phase_glu(const Params& p, int mrows, char* smem) {
;   TILE_IDS; (void)tid;
;   bf16_t* P = WS_BF(p, OFF_P);
;   const bf16_t* W = WS_BF(p, OFF_W) + W_GLU;
;   for (TileIter ti(mrows / 128, 4, 4, 4); ti.valid(); ti.next()) {
;     int tm, tn; ti.get(tm, tn);
;     f32x4 acc[4][4];
.Lgl_exit:
	s_waitcnt vmcnt(0) lgkmcnt(0)
	v_readlane_b32 s40, v249, 0
	v_readlane_b32 s41, v249, 1
	v_readlane_b32 s42, v249, 2
	v_readlane_b32 s43, v249, 3
	v_readlane_b32 s44, v249, 4
	v_readlane_b32 s45, v249, 5
	v_readlane_b32 s46, v249, 6
	v_readlane_b32 s47, v249, 7
	v_mov_b32_e32 v92, s40
	v_mov_b32_e32 v93, s41
	v_mov_b32_e32 v94, s42
	v_mov_b32_e32 v95, s43
	v_mov_b32_e32 v96, s44
	v_mov_b32_e32 v97, s45
	v_mov_b32_e32 v98, s46
	v_mov_b32_e32 v99, s47
	v_readlane_b32 s40, v249, 8
	v_readlane_b32 s41, v249, 9
	v_readlane_b32 s42, v249, 10
	v_readlane_b32 s43, v249, 11
	v_readlane_b32 s44, v249, 12
	v_readlane_b32 s45, v249, 13
	v_readlane_b32 s46, v249, 14
	v_readlane_b32 s47, v249, 15
	v_mov_b32_e32 v100, s40
	v_mov_b32_e32 v101, s41
	v_mov_b32_e32 v102, s42
	v_mov_b32_e32 v103, s43
	v_mov_b32_e32 v104, s44
	v_mov_b32_e32 v105, s45
	v_mov_b32_e32 v106, s46
	v_mov_b32_e32 v107, s47
	v_readlane_b32 s40, v249, 16
	v_readlane_b32 s41, v249, 17
	v_readlane_b32 s42, v249, 18
	v_readlane_b32 s43, v249, 19
	v_readlane_b32 s44, v249, 20
	v_readlane_b32 s45, v249, 21
	v_readlane_b32 s46, v249, 22
	v_readlane_b32 s47, v249, 23
	v_mov_b32_e32 v108, s40
	v_mov_b32_e32 v109, s41
	v_mov_b32_e32 v110, s42
	v_mov_b32_e32 v111, s43
	v_mov_b32_e32 v112, s44
	v_mov_b32_e32 v113, s45
	v_mov_b32_e32 v114, s46
	v_mov_b32_e32 v115, s47
	v_readlane_b32 s40, v249, 24
	v_readlane_b32 s41, v249, 25
	v_readlane_b32 s42, v249, 26
	v_readlane_b32 s43, v249, 27
	v_readlane_b32 s44, v249, 28
	v_readlane_b32 s45, v249, 29
	v_readlane_b32 s46, v249, 30
	v_readlane_b32 s47, v249, 31
	v_mov_b32_e32 v116, s40
	v_mov_b32_e32 v117, s41
	v_mov_b32_e32 v118, s42
	v_mov_b32_e32 v119, s43
	v_mov_b32_e32 v120, s44
	v_mov_b32_e32 v121, s45
	v_mov_b32_e32 v122, s46
	v_mov_b32_e32 v123, s47
	v_readlane_b32 s40, v249, 32
	v_readlane_b32 s41, v249, 33
	v_readlane_b32 s42, v249, 34
	v_readlane_b32 s43, v249, 35
	v_readlane_b32 s44, v249, 36
	v_readlane_b32 s45, v249, 37
	v_readlane_b32 s46, v249, 38
	v_readlane_b32 s47, v249, 39
	v_mov_b32_e32 v124, s40
	v_mov_b32_e32 v125, s41
	v_mov_b32_e32 v126, s42
	v_mov_b32_e32 v127, s43
	v_mov_b32_e32 v128, s44
	v_mov_b32_e32 v129, s45
	v_mov_b32_e32 v130, s46
	v_mov_b32_e32 v131, s47
	v_readlane_b32 s40, v249, 40
	v_readlane_b32 s41, v249, 41
	s_nop 1
	v_mov_b32_e32 v132, s40
	v_mov_b32_e32 v133, s41
.LBB0_93:
	s_mov_b64 s[40:41], 0
